# filler KV-cache conversion items (hl=0 and hl=2 copies): 16 serialized load-convert-store round trips batched into one round trip (15 loads issued together, cvt_pk, stores)
# speedup vs baseline: 1.0144x; 1.0144x over previous
.LBB0_138:
	s_or_b64 exec, exec, s[48:49]
	s_cbranch_vccnz .Lkvba_ld
	v_mov_b32_e32 v50, 0
	v_mov_b32_e32 v51, 0
	v_mov_b32_e32 v52, 0
	v_mov_b32_e32 v53, 0
	v_mov_b32_e32 v54, 0
	v_mov_b32_e32 v55, 0
	v_mov_b32_e32 v56, 0
	v_mov_b32_e32 v57, 0
	v_mov_b32_e32 v58, 0
	v_mov_b32_e32 v59, 0
	v_mov_b32_e32 v60, 0
	v_mov_b32_e32 v61, 0
	v_mov_b32_e32 v62, 0
	v_mov_b32_e32 v63, 0
	v_mov_b32_e32 v64, 0
	v_mov_b32_e32 v65, 0
	v_mov_b32_e32 v66, 0
	v_mov_b32_e32 v67, 0
	v_mov_b32_e32 v68, 0
	v_mov_b32_e32 v69, 0
	v_mov_b32_e32 v70, 0
	v_mov_b32_e32 v71, 0
	v_mov_b32_e32 v72, 0
	v_mov_b32_e32 v73, 0
	v_mov_b32_e32 v74, 0
	v_mov_b32_e32 v75, 0
	v_mov_b32_e32 v76, 0
	v_mov_b32_e32 v77, 0
	v_mov_b32_e32 v78, 0
	v_mov_b32_e32 v79, 0
	v_mov_b32_e32 v80, 0
	v_mov_b32_e32 v81, 0
	v_mov_b32_e32 v82, 0
	v_mov_b32_e32 v83, 0
	v_mov_b32_e32 v84, 0
	v_mov_b32_e32 v85, 0
	v_mov_b32_e32 v86, 0
	v_mov_b32_e32 v87, 0
	v_mov_b32_e32 v88, 0
	v_mov_b32_e32 v89, 0
	v_mov_b32_e32 v90, 0
	v_mov_b32_e32 v91, 0
	v_mov_b32_e32 v92, 0
	v_mov_b32_e32 v93, 0
	v_mov_b32_e32 v94, 0
	v_mov_b32_e32 v95, 0
	v_mov_b32_e32 v96, 0
	v_mov_b32_e32 v97, 0
	v_mov_b32_e32 v98, 0
	v_mov_b32_e32 v99, 0
	v_mov_b32_e32 v100, 0
	v_mov_b32_e32 v101, 0
	v_mov_b32_e32 v102, 0
	v_mov_b32_e32 v103, 0
	v_mov_b32_e32 v104, 0
	v_mov_b32_e32 v105, 0
	v_mov_b32_e32 v106, 0
	v_mov_b32_e32 v107, 0
	v_mov_b32_e32 v108, 0
	v_mov_b32_e32 v109, 0
.Lkvba_ld:
	s_and_saveexec_b64 s[98:99], vcc
	v_mov_b32_e32 v9, v1
	v_lshl_add_u64 v[110:111], v[24:25], 0, v[8:9]
	s_mov_b64 s[100:101], 0x1000
	v_lshl_add_u64 v[112:113], v[110:111], 0, s[100:101]
	v_lshl_add_u64 v[114:115], v[112:113], 0, s[100:101]
	v_lshl_add_u64 v[116:117], v[114:115], 0, s[100:101]
	global_load_dwordx4 v[50:53], v[110:111], off offset:1024
	global_load_dwordx4 v[54:57], v[110:111], off offset:2048
	global_load_dwordx4 v[58:61], v[110:111], off offset:3072
	global_load_dwordx4 v[62:65], v[112:113], off
	global_load_dwordx4 v[66:69], v[112:113], off offset:1024
	global_load_dwordx4 v[70:73], v[112:113], off offset:2048
	global_load_dwordx4 v[74:77], v[112:113], off offset:3072
	global_load_dwordx4 v[78:81], v[114:115], off
	global_load_dwordx4 v[82:85], v[114:115], off offset:1024
	global_load_dwordx4 v[86:89], v[114:115], off offset:2048
	global_load_dwordx4 v[90:93], v[114:115], off offset:3072
	global_load_dwordx4 v[94:97], v[116:117], off
	global_load_dwordx4 v[98:101], v[116:117], off offset:1024
	global_load_dwordx4 v[102:105], v[116:117], off offset:2048
	global_load_dwordx4 v[106:109], v[116:117], off offset:3072
	s_or_b64 exec, exec, s[98:99]
	s_load_dwordx2 s[4:5], s[0:1], 0xd0
	v_cndmask_b32_e64 v0, 0, 2, s[38:39]
	v_or_b32_e32 v0, v0, v21
	s_mov_b32 s8, 0x2100000
	v_mul_lo_u32 v0, v0, s8
	s_waitcnt lgkmcnt(0)
	v_lshl_add_u64 v[22:23], s[4:5], 0, v[0:1]
	v_mul_u32_u24_e32 v0, 0x210000, v20
	v_lshlrev_b32_e32 v0, 1, v0
	v_lshlrev_b32_e32 v36, 12, v3
	v_lshl_add_u64 v[20:21], v[22:23], 0, v[0:1]
	s_mov_b64 s[4:5], 0x9200000
	v_lshl_add_u64 v[20:21], v[20:21], 0, s[4:5]
	v_lshlrev_b32_e32 v0, 1, v36
	v_lshl_add_u64 v[22:23], v[20:21], 0, v[0:1]
	s_waitcnt vmcnt(0)
	v_bfe_u32 v0, v4, 16, 1
	v_add3_u32 v0, v4, v0, s91
	v_bfe_u32 v3, v5, 16, 1
	v_lshrrev_b32_e32 v0, 16, v0
	v_add3_u32 v3, v5, v3, s91
	v_and_or_b32 v4, v3, s92, v0
	v_bfe_u32 v0, v6, 16, 1
	v_add3_u32 v0, v6, v0, s91
	v_bfe_u32 v3, v7, 16, 1
	v_lshrrev_b32_e32 v0, 16, v0
	v_add3_u32 v3, v7, v3, s91
	v_and_or_b32 v5, v3, s92, v0
	v_lshlrev_b32_e32 v0, 3, v10
	v_lshl_add_u64 v[22:23], v[22:23], 0, v[0:1]
	global_store_dwordx2 v[22:23], v[4:5], off
	s_mov_b64 s[100:101], 0x1000
	v_lshl_add_u64 v[118:119], v[22:23], 0, s[100:101]
	v_cvt_pk_bf16_f32 v50, v50, v51
	v_cvt_pk_bf16_f32 v51, v52, v53
	global_store_dwordx2 v[22:23], v[50:51], off offset:512
	v_cvt_pk_bf16_f32 v54, v54, v55
	v_cvt_pk_bf16_f32 v55, v56, v57
	global_store_dwordx2 v[22:23], v[54:55], off offset:1024
	v_cvt_pk_bf16_f32 v58, v58, v59
	v_cvt_pk_bf16_f32 v59, v60, v61
	global_store_dwordx2 v[22:23], v[58:59], off offset:1536
	v_cvt_pk_bf16_f32 v62, v62, v63
	v_cvt_pk_bf16_f32 v63, v64, v65
	global_store_dwordx2 v[22:23], v[62:63], off offset:2048
	v_cvt_pk_bf16_f32 v66, v66, v67
	v_cvt_pk_bf16_f32 v67, v68, v69
	global_store_dwordx2 v[22:23], v[66:67], off offset:2560
	v_cvt_pk_bf16_f32 v70, v70, v71
	v_cvt_pk_bf16_f32 v71, v72, v73
	global_store_dwordx2 v[22:23], v[70:71], off offset:3072
	v_cvt_pk_bf16_f32 v74, v74, v75
	v_cvt_pk_bf16_f32 v75, v76, v77
	global_store_dwordx2 v[22:23], v[74:75], off offset:3584
	v_cvt_pk_bf16_f32 v78, v78, v79
	v_cvt_pk_bf16_f32 v79, v80, v81
	global_store_dwordx2 v[118:119], v[78:79], off
	v_cvt_pk_bf16_f32 v82, v82, v83
	v_cvt_pk_bf16_f32 v83, v84, v85
	global_store_dwordx2 v[118:119], v[82:83], off offset:512
	v_cvt_pk_bf16_f32 v86, v86, v87
	v_cvt_pk_bf16_f32 v87, v88, v89
	global_store_dwordx2 v[118:119], v[86:87], off offset:1024
	v_cvt_pk_bf16_f32 v90, v90, v91
	v_cvt_pk_bf16_f32 v91, v92, v93
	global_store_dwordx2 v[118:119], v[90:91], off offset:1536
	v_cvt_pk_bf16_f32 v94, v94, v95
	v_cvt_pk_bf16_f32 v95, v96, v97
	global_store_dwordx2 v[118:119], v[94:95], off offset:2048
	v_cvt_pk_bf16_f32 v98, v98, v99
	v_cvt_pk_bf16_f32 v99, v100, v101
	global_store_dwordx2 v[118:119], v[98:99], off offset:2560
	v_cvt_pk_bf16_f32 v102, v102, v103
	v_cvt_pk_bf16_f32 v103, v104, v105
	global_store_dwordx2 v[118:119], v[102:103], off offset:3072
	v_cvt_pk_bf16_f32 v106, v106, v107
	v_cvt_pk_bf16_f32 v107, v108, v109
	global_store_dwordx2 v[118:119], v[106:107], off offset:3584

.LBB0_263:
	s_or_b64 exec, exec, s[50:51]
	s_cbranch_vccnz .Lkvbb_ld
	v_mov_b32_e32 v50, 0
	v_mov_b32_e32 v51, 0
	v_mov_b32_e32 v52, 0
	v_mov_b32_e32 v53, 0
	v_mov_b32_e32 v54, 0
	v_mov_b32_e32 v55, 0
	v_mov_b32_e32 v56, 0
	v_mov_b32_e32 v57, 0
	v_mov_b32_e32 v58, 0
	v_mov_b32_e32 v59, 0
	v_mov_b32_e32 v60, 0
	v_mov_b32_e32 v61, 0
	v_mov_b32_e32 v62, 0
	v_mov_b32_e32 v63, 0
	v_mov_b32_e32 v64, 0
	v_mov_b32_e32 v65, 0
	v_mov_b32_e32 v66, 0
	v_mov_b32_e32 v67, 0
	v_mov_b32_e32 v68, 0
	v_mov_b32_e32 v69, 0
	v_mov_b32_e32 v70, 0
	v_mov_b32_e32 v71, 0
	v_mov_b32_e32 v72, 0
	v_mov_b32_e32 v73, 0
	v_mov_b32_e32 v74, 0
	v_mov_b32_e32 v75, 0
	v_mov_b32_e32 v76, 0
	v_mov_b32_e32 v77, 0
	v_mov_b32_e32 v78, 0
	v_mov_b32_e32 v79, 0
	v_mov_b32_e32 v80, 0
	v_mov_b32_e32 v81, 0
	v_mov_b32_e32 v82, 0
	v_mov_b32_e32 v83, 0
	v_mov_b32_e32 v84, 0
	v_mov_b32_e32 v85, 0
	v_mov_b32_e32 v86, 0
	v_mov_b32_e32 v87, 0
	v_mov_b32_e32 v88, 0
	v_mov_b32_e32 v89, 0
	v_mov_b32_e32 v90, 0
	v_mov_b32_e32 v91, 0
	v_mov_b32_e32 v92, 0
	v_mov_b32_e32 v93, 0
	v_mov_b32_e32 v94, 0
	v_mov_b32_e32 v95, 0
	v_mov_b32_e32 v96, 0
	v_mov_b32_e32 v97, 0
	v_mov_b32_e32 v98, 0
	v_mov_b32_e32 v99, 0
	v_mov_b32_e32 v100, 0
	v_mov_b32_e32 v101, 0
	v_mov_b32_e32 v102, 0
	v_mov_b32_e32 v103, 0
	v_mov_b32_e32 v104, 0
	v_mov_b32_e32 v105, 0
	v_mov_b32_e32 v106, 0
	v_mov_b32_e32 v107, 0
	v_mov_b32_e32 v108, 0
	v_mov_b32_e32 v109, 0
.Lkvbb_ld:
	s_and_saveexec_b64 s[98:99], vcc
	v_mov_b32_e32 v9, v1
	v_lshl_add_u64 v[110:111], v[24:25], 0, v[8:9]
	s_mov_b64 s[100:101], 0x1000
	v_lshl_add_u64 v[112:113], v[110:111], 0, s[100:101]
	v_lshl_add_u64 v[114:115], v[112:113], 0, s[100:101]
	v_lshl_add_u64 v[116:117], v[114:115], 0, s[100:101]
	global_load_dwordx4 v[50:53], v[110:111], off offset:1024
	global_load_dwordx4 v[54:57], v[110:111], off offset:2048
	global_load_dwordx4 v[58:61], v[110:111], off offset:3072
	global_load_dwordx4 v[62:65], v[112:113], off
	global_load_dwordx4 v[66:69], v[112:113], off offset:1024
	global_load_dwordx4 v[70:73], v[112:113], off offset:2048
	global_load_dwordx4 v[74:77], v[112:113], off offset:3072
	global_load_dwordx4 v[78:81], v[114:115], off
	global_load_dwordx4 v[82:85], v[114:115], off offset:1024
	global_load_dwordx4 v[86:89], v[114:115], off offset:2048
	global_load_dwordx4 v[90:93], v[114:115], off offset:3072
	global_load_dwordx4 v[94:97], v[116:117], off
	global_load_dwordx4 v[98:101], v[116:117], off offset:1024
	global_load_dwordx4 v[102:105], v[116:117], off offset:2048
	global_load_dwordx4 v[106:109], v[116:117], off offset:3072
	s_or_b64 exec, exec, s[98:99]
	s_load_dwordx2 s[4:5], s[0:1], 0xd0
	v_cndmask_b32_e64 v0, 0, v217, s[40:41]
	v_and_b32_e32 v3, 0xffff, v3
	v_lshlrev_b32_e32 v36, 12, v20
	s_waitcnt lgkmcnt(0)
	v_lshl_add_u64 v[20:21], s[4:5], 0, v[0:1]
	s_mov_b32 s4, 0x420000
	v_mad_u64_u32 v[20:21], s[4:5], v3, s4, v[20:21]
	s_mov_b64 s[4:5], 0x9200000
	s_nop 0
	v_lshl_add_u64 v[20:21], v[20:21], 0, s[4:5]
	v_lshlrev_b32_e32 v0, 1, v36
	v_lshl_add_u64 v[22:23], v[20:21], 0, v[0:1]
	s_waitcnt vmcnt(0)
	v_bfe_u32 v0, v4, 16, 1
	v_add3_u32 v0, v4, v0, s91
	v_bfe_u32 v3, v5, 16, 1
	v_lshrrev_b32_e32 v0, 16, v0
	v_add3_u32 v3, v5, v3, s91
	v_and_or_b32 v4, v3, s92, v0
	v_bfe_u32 v0, v6, 16, 1
	v_add3_u32 v0, v6, v0, s91
	v_bfe_u32 v3, v7, 16, 1
	v_lshrrev_b32_e32 v0, 16, v0
	v_add3_u32 v3, v7, v3, s91
	v_and_or_b32 v5, v3, s92, v0
	v_lshlrev_b32_e32 v0, 3, v10
	v_lshl_add_u64 v[22:23], v[22:23], 0, v[0:1]
	global_store_dwordx2 v[22:23], v[4:5], off
	s_mov_b64 s[100:101], 0x1000
	v_lshl_add_u64 v[118:119], v[22:23], 0, s[100:101]
	v_cvt_pk_bf16_f32 v50, v50, v51
	v_cvt_pk_bf16_f32 v51, v52, v53
	global_store_dwordx2 v[22:23], v[50:51], off offset:512
	v_cvt_pk_bf16_f32 v54, v54, v55
	v_cvt_pk_bf16_f32 v55, v56, v57
	global_store_dwordx2 v[22:23], v[54:55], off offset:1024
	v_cvt_pk_bf16_f32 v58, v58, v59
	v_cvt_pk_bf16_f32 v59, v60, v61
	global_store_dwordx2 v[22:23], v[58:59], off offset:1536
	v_cvt_pk_bf16_f32 v62, v62, v63
	v_cvt_pk_bf16_f32 v63, v64, v65
	global_store_dwordx2 v[22:23], v[62:63], off offset:2048
	v_cvt_pk_bf16_f32 v66, v66, v67
	v_cvt_pk_bf16_f32 v67, v68, v69
	global_store_dwordx2 v[22:23], v[66:67], off offset:2560
	v_cvt_pk_bf16_f32 v70, v70, v71
	v_cvt_pk_bf16_f32 v71, v72, v73
	global_store_dwordx2 v[22:23], v[70:71], off offset:3072
	v_cvt_pk_bf16_f32 v74, v74, v75
	v_cvt_pk_bf16_f32 v75, v76, v77
	global_store_dwordx2 v[22:23], v[74:75], off offset:3584
	v_cvt_pk_bf16_f32 v78, v78, v79
	v_cvt_pk_bf16_f32 v79, v80, v81
	global_store_dwordx2 v[118:119], v[78:79], off
	v_cvt_pk_bf16_f32 v82, v82, v83
	v_cvt_pk_bf16_f32 v83, v84, v85
	global_store_dwordx2 v[118:119], v[82:83], off offset:512
	v_cvt_pk_bf16_f32 v86, v86, v87
	v_cvt_pk_bf16_f32 v87, v88, v89
	global_store_dwordx2 v[118:119], v[86:87], off offset:1024
	v_cvt_pk_bf16_f32 v90, v90, v91
	v_cvt_pk_bf16_f32 v91, v92, v93
	global_store_dwordx2 v[118:119], v[90:91], off offset:1536
	v_cvt_pk_bf16_f32 v94, v94, v95
	v_cvt_pk_bf16_f32 v95, v96, v97
	global_store_dwordx2 v[118:119], v[94:95], off offset:2048
	v_cvt_pk_bf16_f32 v98, v98, v99
	v_cvt_pk_bf16_f32 v99, v100, v101
	global_store_dwordx2 v[118:119], v[98:99], off offset:2560
	v_cvt_pk_bf16_f32 v102, v102, v103
	v_cvt_pk_bf16_f32 v103, v104, v105
	global_store_dwordx2 v[118:119], v[102:103], off offset:3072
	v_cvt_pk_bf16_f32 v106, v106, v107
	v_cvt_pk_bf16_f32 v107, v108, v109
	global_store_dwordx2 v[118:119], v[106:107], off offset:3584
